# PRO: Fourier-mixer weight transform (C256|S256 x fnet_w) item loop rewritten as f32-operand MFMA 16x16x4 mini-GEMM with a compact 256-entry twiddle table in LDS
# speedup vs baseline: 1.0084x; 1.0084x over previous
.LBB0_1074:
	s_lshl_b32 s0, s83, 4
	s_ashr_i32 s29, s83, 6
	s_and_b32 s30, s0, 0x3f0
	s_lshl_b32 s8, s30, 2
	s_lshl_b32 s31, s29, 20
	s_add_u32 s8, s8, s31
	s_mov_b32 s9, 0
	v_lshrrev_b32_e32 v6, 4, v184
	v_lshlrev_b32_e32 v6, 12, v6
	v_mov_b32_e32 v7, 0
	v_lshl_add_u64 v[6:7], v[4:5], 0, v[6:7]
	v_lshl_add_u64 v[6:7], v[6:7], 0, s[8:9]
	s_mov_b64 s[22:23], 0x20000
	global_load_dword v8, v[6:7], off
	v_lshl_add_u64 v[6:7], v[6:7], 0, s[22:23]
	global_load_dword v9, v[6:7], off
	v_lshl_add_u64 v[6:7], v[6:7], 0, s[22:23]
	global_load_dword v10, v[6:7], off
	v_lshl_add_u64 v[6:7], v[6:7], 0, s[22:23]
	global_load_dword v11, v[6:7], off
	v_lshl_add_u64 v[6:7], v[6:7], 0, s[22:23]
	global_load_dword v12, v[6:7], off
	v_lshl_add_u64 v[6:7], v[6:7], 0, s[22:23]
	global_load_dword v13, v[6:7], off
	v_lshl_add_u64 v[6:7], v[6:7], 0, s[22:23]
	global_load_dword v14, v[6:7], off
	v_lshl_add_u64 v[6:7], v[6:7], 0, s[22:23]
	global_load_dword v15, v[6:7], off
	v_cmp_gt_u32_e32 vcc, 0x100, v184
	s_and_saveexec_b64 s[24:25], vcc
	v_lshlrev_b32_e32 v16, 7, v184
	ds_read_b64 v[18:19], v16
	v_lshlrev_b32_e32 v17, 3, v184
	s_waitcnt lgkmcnt(0)
	ds_write_b64 v17, v[18:19] offset:49152
	s_or_b64 exec, exec, s[24:25]
	v_and_b32_e32 v20, 63, v184
	v_lshrrev_b32_e32 v21, 6, v184
	v_and_b32_e32 v24, 15, v20
	v_lshrrev_b32_e32 v25, 4, v20
	v_lshl_add_u32 v29, v21, 5, v24
	v_add_u32_e32 v30, 16, v29
	v_mul_u32_u24_e32 v31, v29, v25
	v_mul_u32_u24_e32 v32, v30, v25
	v_and_b32_e32 v31, 0xff, v31
	v_and_b32_e32 v32, 0xff, v32
	v_lshlrev_b32_e32 v31, 3, v31
	v_lshlrev_b32_e32 v32, 3, v32
	v_lshlrev_b32_e32 v33, 5, v29
	v_lshlrev_b32_e32 v34, 5, v30
	v_and_b32_e32 v33, 0x7f8, v33
	v_and_b32_e32 v34, 0x7f8, v34
	v_lshl_add_u32 v35, v20, 2, s28
	v_mov_b32_e32 v36, 0
	v_mov_b32_e32 v37, 0
	v_mov_b32_e32 v38, 0
	v_mov_b32_e32 v39, 0
	v_mov_b32_e32 v40, 0
	v_mov_b32_e32 v41, 0
	v_mov_b32_e32 v42, 0
	v_mov_b32_e32 v43, 0
	v_mov_b32_e32 v44, 0
	v_mov_b32_e32 v45, 0
	v_mov_b32_e32 v46, 0
	v_mov_b32_e32 v47, 0
	v_mov_b32_e32 v48, 0
	v_mov_b32_e32 v49, 0
	v_mov_b32_e32 v50, 0
	v_mov_b32_e32 v51, 0
	s_waitcnt vmcnt(0)
	ds_write_b32 v27, v8 offset:0
	ds_write_b32 v27, v9 offset:2048
	ds_write_b32 v27, v10 offset:4096
	ds_write_b32 v27, v11 offset:6144
	ds_write_b32 v27, v12 offset:8192
	ds_write_b32 v27, v13 offset:10240
	ds_write_b32 v27, v14 offset:12288
	ds_write_b32 v27, v15 offset:14336
	s_waitcnt lgkmcnt(0)
	s_barrier
	ds_read_b32 v52, v35
	ds_read_b64 v[54:55], v31 offset:49152
	ds_read_b64 v[56:57], v32 offset:49152
	v_add_u32_e32 v31, v31, v33
	v_add_u32_e32 v32, v32, v34
	v_and_b32_e32 v31, 0x7f8, v31
	v_and_b32_e32 v32, 0x7f8, v32
	s_movk_i32 s0, 32
.Lwcs_kloop:
	ds_read_b32 v53, v35 offset:256
	ds_read_b64 v[58:59], v31 offset:49152
	ds_read_b64 v[60:61], v32 offset:49152
	v_add_u32_e32 v31, v31, v33
	v_add_u32_e32 v32, v32, v34
	v_and_b32_e32 v31, 0x7f8, v31
	v_and_b32_e32 v32, 0x7f8, v32
	s_waitcnt lgkmcnt(3)
	v_mfma_f32_16x16x4_f32 v[36:39], v54, v52, v[36:39]
	v_mfma_f32_16x16x4_f32 v[40:43], v55, v52, v[40:43]
	v_mfma_f32_16x16x4_f32 v[44:47], v56, v52, v[44:47]
	v_mfma_f32_16x16x4_f32 v[48:51], v57, v52, v[48:51]
	ds_read_b32 v52, v35 offset:512
	ds_read_b64 v[54:55], v31 offset:49152
	ds_read_b64 v[56:57], v32 offset:49152
	v_add_u32_e32 v31, v31, v33
	v_add_u32_e32 v32, v32, v34
	v_and_b32_e32 v31, 0x7f8, v31
	v_and_b32_e32 v32, 0x7f8, v32
	v_add_u32_e32 v35, 0x200, v35
	s_waitcnt lgkmcnt(3)
	v_mfma_f32_16x16x4_f32 v[36:39], v58, v53, v[36:39]
	v_mfma_f32_16x16x4_f32 v[40:43], v59, v53, v[40:43]
	v_mfma_f32_16x16x4_f32 v[44:47], v60, v53, v[44:47]
	v_mfma_f32_16x16x4_f32 v[48:51], v61, v53, v[48:51]
	s_sub_i32 s0, s0, 1
	s_cmp_lg_u32 s0, 0
	s_cbranch_scc1 .Lwcs_kloop
	v_readlane_b32 s0, v251, 34
	v_readlane_b32 s1, v251, 35
	v_or_b32_e32 v6, s30, v24
	v_lshlrev_b32_e32 v6, 11, v6
	v_lshlrev_b32_e32 v7, 2, v25
	v_lshl_add_u32 v7, v21, 5, v7
	s_lshl_b32 s8, s29, 8
	v_add_u32_e32 v7, s8, v7
	v_lshl_add_u32 v6, v7, 1, v6
	v_mov_b32_e32 v7, 0
	s_waitcnt lgkmcnt(0)
	s_nop 15
	s_nop 15
	s_nop 15
	v_lshl_add_u64 v[6:7], s[0:1], 0, v[6:7]
	s_mov_b64 s[22:23], 0x200000
	v_lshl_add_u64 v[8:9], v[6:7], 0, s[22:23]
	v_mul_f32_e32 v36, 0x3d800000, v36
	v_mul_f32_e32 v37, 0x3d800000, v37
	v_mul_f32_e32 v38, 0x3d800000, v38
	v_mul_f32_e32 v39, 0x3d800000, v39
	v_mul_f32_e32 v40, 0x3d800000, v40
	v_mul_f32_e32 v41, 0x3d800000, v41
	v_mul_f32_e32 v42, 0x3d800000, v42
	v_mul_f32_e32 v43, 0x3d800000, v43
	v_mul_f32_e32 v44, 0x3d800000, v44
	v_mul_f32_e32 v45, 0x3d800000, v45
	v_mul_f32_e32 v46, 0x3d800000, v46
	v_mul_f32_e32 v47, 0x3d800000, v47
	v_mul_f32_e32 v48, 0x3d800000, v48
	v_mul_f32_e32 v49, 0x3d800000, v49
	v_mul_f32_e32 v50, 0x3d800000, v50
	v_mul_f32_e32 v51, 0x3d800000, v51
	v_cvt_pk_bf16_f32 v62, v36, v37
	v_cvt_pk_bf16_f32 v63, v38, v39
	v_cvt_pk_bf16_f32 v64, v40, v41
	v_cvt_pk_bf16_f32 v65, v42, v43
	v_cvt_pk_bf16_f32 v66, v44, v45
	v_cvt_pk_bf16_f32 v67, v46, v47
	v_cvt_pk_bf16_f32 v68, v48, v49
	v_cvt_pk_bf16_f32 v69, v50, v51
	global_store_dwordx2 v[6:7], v[62:63], off
	global_store_dwordx2 v[8:9], v[64:65], off
	global_store_dwordx2 v[6:7], v[66:67], off offset:32
	global_store_dwordx2 v[8:9], v[68:69], off offset:32
	s_add_i32 s83, s83, s90
	s_cmpk_gt_i32 s83, 0xff
	s_barrier
	s_cbranch_scc0 .LBB0_1074
